# gated-merge GEMM epilogue: gate loads software-pipelined four loads ahead with pre-computed addresses (on top of the pipelined mid-K hook)
# speedup vs baseline: 1.0035x; 1.0035x over previous
.LBB0_266:
	v_mov_b32_e32 v240, v1
	v_mov_b32_e32 v241, v154
	s_add_i32 s93, s93, s64
	s_or_b32 s0, s92, s65
	v_mov_b64_e32 v[242:243], s[10:11]
	v_add_u32_e32 v244, s93, v240
	v_lshl_add_u32 v240, v241, 3, s0
	v_mad_i64_i32 v[246:247], s[20:21], v244, s24, v[242:243]
	s_mov_b64 s[18:19], 0x1000
	v_ashrrev_i32_e32 v241, 31, v240
	v_lshl_add_u64 v[246:247], v[246:247], 0, s[18:19]
	v_lshlrev_b64 v[248:249], 1, v[240:241]
	v_lshl_add_u64 v[250:251], v[246:247], 0, v[248:249]
	v_mov_b32_e32 v200, v250
	v_mov_b32_e32 v201, v251
	v_add_u32_e32 v240, 0x80, v240
	v_ashrrev_i32_e32 v241, 31, v240
	v_lshlrev_b64 v[240:241], 1, v[240:241]
	v_lshl_add_u64 v[246:247], v[246:247], 0, v[240:241]
	v_mov_b32_e32 v202, v246
	v_mov_b32_e32 v203, v247
	v_add_u32_e32 v246, 16, v244
	v_mad_i64_i32 v[246:247], s[20:21], v246, s24, v[242:243]
	v_lshl_add_u64 v[246:247], v[246:247], 0, s[18:19]
	v_lshl_add_u64 v[250:251], v[246:247], 0, v[248:249]
	v_mov_b32_e32 v204, v250
	v_mov_b32_e32 v205, v251
	v_lshl_add_u64 v[246:247], v[246:247], 0, v[240:241]
	v_mov_b32_e32 v206, v246
	v_mov_b32_e32 v207, v247
	v_add_u32_e32 v246, 32, v244
	v_mad_i64_i32 v[246:247], s[20:21], v246, s24, v[242:243]
	v_lshl_add_u64 v[246:247], v[246:247], 0, s[18:19]
	v_lshl_add_u64 v[250:251], v[246:247], 0, v[248:249]
	v_mov_b32_e32 v208, v250
	v_mov_b32_e32 v209, v251
	v_lshl_add_u64 v[246:247], v[246:247], 0, v[240:241]
	v_mov_b32_e32 v210, v246
	v_mov_b32_e32 v211, v247
	v_add_u32_e32 v246, 48, v244
	v_mad_i64_i32 v[246:247], s[20:21], v246, s24, v[242:243]
	v_lshl_add_u64 v[246:247], v[246:247], 0, s[18:19]
	v_lshl_add_u64 v[250:251], v[246:247], 0, v[248:249]
	v_mov_b32_e32 v212, v250
	v_mov_b32_e32 v213, v251
	v_lshl_add_u64 v[246:247], v[246:247], 0, v[240:241]
	v_mov_b32_e32 v214, v246
	v_mov_b32_e32 v215, v247
	v_add_u32_e32 v246, 0x80, v244
	v_mad_i64_i32 v[246:247], s[20:21], v246, s24, v[242:243]
	v_lshl_add_u64 v[246:247], v[246:247], 0, s[18:19]
	v_lshl_add_u64 v[250:251], v[246:247], 0, v[248:249]
	v_mov_b32_e32 v216, v250
	v_mov_b32_e32 v217, v251
	v_lshl_add_u64 v[246:247], v[246:247], 0, v[240:241]
	v_mov_b32_e32 v218, v246
	v_mov_b32_e32 v219, v247
	v_add_u32_e32 v246, 0x90, v244
	v_mad_i64_i32 v[246:247], s[20:21], v246, s24, v[242:243]
	v_lshl_add_u64 v[246:247], v[246:247], 0, s[18:19]
	v_lshl_add_u64 v[250:251], v[246:247], 0, v[248:249]
	v_mov_b32_e32 v220, v250
	v_mov_b32_e32 v221, v251
	v_lshl_add_u64 v[246:247], v[246:247], 0, v[240:241]
	v_mov_b32_e32 v222, v246
	v_mov_b32_e32 v223, v247
	v_add_u32_e32 v246, 0xa0, v244
	v_mad_i64_i32 v[246:247], s[20:21], v246, s24, v[242:243]
	v_lshl_add_u64 v[246:247], v[246:247], 0, s[18:19]
	v_lshl_add_u64 v[250:251], v[246:247], 0, v[248:249]
	v_mov_b32_e32 v226, v250
	v_mov_b32_e32 v227, v251
	v_lshl_add_u64 v[246:247], v[246:247], 0, v[240:241]
	v_mov_b32_e32 v232, v246
	v_mov_b32_e32 v233, v247
	v_add_u32_e32 v244, 0xb0, v244
	v_mad_i64_i32 v[242:243], s[20:21], v244, s24, v[242:243]
	v_lshl_add_u64 v[242:243], v[242:243], 0, s[18:19]
	v_lshl_add_u64 v[244:245], v[242:243], 0, v[248:249]
	v_mov_b32_e32 v166, v244
	v_mov_b32_e32 v167, v245
	v_lshl_add_u64 v[240:241], v[242:243], 0, v[240:241]
	v_mov_b32_e32 v252, v240
	v_mov_b32_e32 v253, v241
	v_mov_b32_e32 v130, v1
	v_mov_b32_e32 v131, v154
	v_mov_b64_e32 v[134:135], s[10:11]
	v_add_u32_e32 v132, s93, v130
	v_lshl_add_u32 v136, v131, 3, s0
	v_mad_i64_i32 v[130:131], s[0:1], v132, s24, v[134:135]
	v_ashrrev_i32_e32 v137, 31, v136
	v_lshl_add_u64 v[160:161], v[130:131], 0, s[18:19]
	v_lshlrev_b64 v[130:131], 1, v[136:137]
	v_lshl_add_u64 v[150:151], v[160:161], 0, v[130:131]
	global_load_dwordx4 v[168:171], v[200:201], off
	global_load_dwordx4 v[172:175], v[202:203], off
	global_load_dwordx4 v[176:179], v[204:205], off
	global_load_dwordx4 v[180:183], v[206:207], off
	global_load_dwordx4 v[184:187], v[208:209], off
	s_waitcnt vmcnt(4)
	v_ashrrev_i32_e32 v133, 31, v132
	v_lshlrev_b64 v[158:159], 11, v[132:133]
	s_and_b64 vcc, exec, s[4:5]
	s_mov_b32 s97, 0x10000
	s_mov_b32 s96, 0x12000
	s_mov_b32 s89, 0x16000
	s_movk_i32 s95, 0x3c0
	s_mov_b32 s92, 0xfe5163ab
	s_mov_b32 s93, 0x3c439041
	s_mov_b32 s94, 0xdb629599
	v_lshlrev_b32_e32 v162, 16, v168
	v_and_b32_e32 v163, 0xffff0000, v168
	v_lshlrev_b32_e32 v150, 16, v169
	v_and_b32_e32 v151, 0xffff0000, v169
	v_lshlrev_b32_e32 v164, 16, v170
	v_and_b32_e32 v165, 0xffff0000, v170
	v_lshlrev_b32_e32 v152, 16, v171
	v_and_b32_e32 v153, 0xffff0000, v171
	v_pk_mul_f32 v[126:127], v[126:127], v[162:163]
	v_pk_mul_f32 v[128:129], v[128:129], v[150:151]
	v_pk_mul_f32 v[150:151], v[124:125], v[152:153]
	v_pk_mul_f32 v[124:125], v[122:123], v[164:165]
	v_cvt_pk_bf16_f32 v122, v126, v127
	v_lshl_add_u64 v[126:127], s[12:13], 0, v[158:159]
	v_cvt_pk_bf16_f32 v123, v128, v129
	v_cvt_pk_bf16_f32 v124, v124, v125
	v_cvt_pk_bf16_f32 v125, v150, v151
	v_lshl_add_u64 v[128:129], v[126:127], 0, v[130:131]
	global_store_dwordx4 v[128:129], v[122:125], off
	s_nop 1
	v_add_u32_e32 v122, 0x80, v136
	v_ashrrev_i32_e32 v123, 31, v122
	v_lshlrev_b64 v[122:123], 1, v[122:123]
	v_lshl_add_u64 v[124:125], v[160:161], 0, v[122:123]
	global_load_dwordx4 v[188:191], v[210:211], off
	s_waitcnt vmcnt(5)
	v_lshlrev_b32_e32 v136, 16, v172
	v_and_b32_e32 v137, 0xffff0000, v172
	v_lshlrev_b32_e32 v124, 16, v173
	v_and_b32_e32 v125, 0xffff0000, v173
	v_lshlrev_b32_e32 v150, 16, v174
	v_and_b32_e32 v151, 0xffff0000, v174
	v_lshlrev_b32_e32 v126, 16, v175
	v_and_b32_e32 v127, 0xffff0000, v175
	v_pk_mul_f32 v[120:121], v[120:121], v[124:125]
	v_pk_mul_f32 v[118:119], v[118:119], v[136:137]
	v_pk_mul_f32 v[124:125], v[116:117], v[126:127]
	v_pk_mul_f32 v[116:117], v[114:115], v[150:151]
	v_cvt_pk_bf16_f32 v114, v118, v119
	v_cvt_pk_bf16_f32 v115, v120, v121
	v_cvt_pk_bf16_f32 v116, v116, v117
	v_cvt_pk_bf16_f32 v117, v124, v125
	global_store_dwordx4 v[128:129], v[114:117], off offset:256
	s_nop 1
	v_add_u32_e32 v114, 16, v132
	v_ashrrev_i32_e32 v115, 31, v114
	v_lshlrev_b64 v[118:119], 11, v[114:115]
	v_mad_i64_i32 v[114:115], s[0:1], v114, s24, v[134:135]
	v_lshl_add_u64 v[120:121], v[114:115], 0, s[18:19]
	v_lshl_add_u64 v[114:115], v[120:121], 0, v[130:131]
	global_load_dwordx4 v[192:195], v[212:213], off
	s_waitcnt vmcnt(6)
	v_lshlrev_b32_e32 v124, 16, v176
	v_and_b32_e32 v125, 0xffff0000, v176
	v_lshlrev_b32_e32 v114, 16, v177
	v_and_b32_e32 v115, 0xffff0000, v177
	v_lshlrev_b32_e32 v126, 16, v178
	v_and_b32_e32 v127, 0xffff0000, v178
	v_lshlrev_b32_e32 v116, 16, v179
	v_and_b32_e32 v117, 0xffff0000, v179
	v_pk_mul_f32 v[110:111], v[110:111], v[124:125]
	v_pk_mul_f32 v[112:113], v[112:113], v[114:115]
	v_pk_mul_f32 v[114:115], v[108:109], v[116:117]
	v_pk_mul_f32 v[108:109], v[106:107], v[126:127]
	v_cvt_pk_bf16_f32 v106, v110, v111
	v_lshl_add_u64 v[110:111], s[12:13], 0, v[118:119]
	v_cvt_pk_bf16_f32 v107, v112, v113
	v_cvt_pk_bf16_f32 v108, v108, v109
	v_cvt_pk_bf16_f32 v109, v114, v115
	v_lshl_add_u64 v[110:111], v[110:111], 0, v[130:131]
	global_store_dwordx4 v[110:111], v[106:109], off
	s_nop 1
	v_lshl_add_u64 v[106:107], v[120:121], 0, v[122:123]
	global_load_dwordx4 v[196:199], v[214:215], off
	s_waitcnt vmcnt(7)
	v_lshlrev_b32_e32 v112, 16, v180
	v_and_b32_e32 v113, 0xffff0000, v180
	v_lshlrev_b32_e32 v106, 16, v181
	v_and_b32_e32 v107, 0xffff0000, v181
	v_lshlrev_b32_e32 v114, 16, v182
	v_and_b32_e32 v115, 0xffff0000, v182
	v_lshlrev_b32_e32 v108, 16, v183
	v_and_b32_e32 v109, 0xffff0000, v183
	v_pk_mul_f32 v[104:105], v[104:105], v[106:107]
	v_pk_mul_f32 v[102:103], v[102:103], v[112:113]
	v_pk_mul_f32 v[106:107], v[100:101], v[108:109]
	v_pk_mul_f32 v[100:101], v[98:99], v[114:115]
	v_cvt_pk_bf16_f32 v98, v102, v103
	v_cvt_pk_bf16_f32 v99, v104, v105
	v_cvt_pk_bf16_f32 v100, v100, v101
	v_cvt_pk_bf16_f32 v101, v106, v107
	global_store_dwordx4 v[110:111], v[98:101], off offset:256
	s_nop 1
	v_add_u32_e32 v98, 32, v132
	v_ashrrev_i32_e32 v99, 31, v98
	v_lshlrev_b64 v[102:103], 11, v[98:99]
	v_mad_i64_i32 v[98:99], s[0:1], v98, s24, v[134:135]
	v_lshl_add_u64 v[104:105], v[98:99], 0, s[18:19]
	v_lshl_add_u64 v[98:99], v[104:105], 0, v[130:131]
	global_load_dwordx4 v[168:171], v[216:217], off
	s_waitcnt vmcnt(8)
	v_lshlrev_b32_e32 v106, 16, v184
	v_and_b32_e32 v107, 0xffff0000, v184
	v_lshlrev_b32_e32 v98, 16, v185
	v_and_b32_e32 v99, 0xffff0000, v185
	v_lshlrev_b32_e32 v108, 16, v186
	v_and_b32_e32 v109, 0xffff0000, v186
	v_lshlrev_b32_e32 v100, 16, v187
	v_and_b32_e32 v101, 0xffff0000, v187
	v_pk_mul_f32 v[94:95], v[94:95], v[106:107]
	v_pk_mul_f32 v[96:97], v[96:97], v[98:99]
	v_pk_mul_f32 v[98:99], v[92:93], v[100:101]
	v_pk_mul_f32 v[92:93], v[90:91], v[108:109]
	v_cvt_pk_bf16_f32 v90, v94, v95
	v_lshl_add_u64 v[94:95], s[12:13], 0, v[102:103]
	v_cvt_pk_bf16_f32 v91, v96, v97
	v_cvt_pk_bf16_f32 v92, v92, v93
	v_cvt_pk_bf16_f32 v93, v98, v99
	v_lshl_add_u64 v[94:95], v[94:95], 0, v[130:131]
	global_store_dwordx4 v[94:95], v[90:93], off
	s_nop 1
	v_lshl_add_u64 v[90:91], v[104:105], 0, v[122:123]
	global_load_dwordx4 v[172:175], v[218:219], off
	s_waitcnt vmcnt(8)
	v_lshlrev_b32_e32 v96, 16, v188
	v_and_b32_e32 v97, 0xffff0000, v188
	v_lshlrev_b32_e32 v90, 16, v189
	v_and_b32_e32 v91, 0xffff0000, v189
	v_lshlrev_b32_e32 v98, 16, v190
	v_and_b32_e32 v99, 0xffff0000, v190
	v_lshlrev_b32_e32 v92, 16, v191
	v_and_b32_e32 v93, 0xffff0000, v191
	v_pk_mul_f32 v[88:89], v[88:89], v[90:91]
	v_pk_mul_f32 v[86:87], v[86:87], v[96:97]
	v_pk_mul_f32 v[90:91], v[84:85], v[92:93]
	v_pk_mul_f32 v[84:85], v[82:83], v[98:99]
	v_cvt_pk_bf16_f32 v82, v86, v87
	v_cvt_pk_bf16_f32 v83, v88, v89
	v_cvt_pk_bf16_f32 v84, v84, v85
	v_cvt_pk_bf16_f32 v85, v90, v91
	global_store_dwordx4 v[94:95], v[82:85], off offset:256
	s_nop 1
	v_add_u32_e32 v82, 48, v132
	v_ashrrev_i32_e32 v83, 31, v82
	v_lshlrev_b64 v[86:87], 11, v[82:83]
	v_mad_i64_i32 v[82:83], s[0:1], v82, s24, v[134:135]
	v_lshl_add_u64 v[88:89], v[82:83], 0, s[18:19]
	v_lshl_add_u64 v[82:83], v[88:89], 0, v[130:131]
	global_load_dwordx4 v[176:179], v[220:221], off
	s_waitcnt vmcnt(8)
	v_lshlrev_b32_e32 v90, 16, v192
	v_and_b32_e32 v91, 0xffff0000, v192
	v_lshlrev_b32_e32 v82, 16, v193
	v_and_b32_e32 v83, 0xffff0000, v193
	v_lshlrev_b32_e32 v92, 16, v194
	v_and_b32_e32 v93, 0xffff0000, v194
	v_lshlrev_b32_e32 v84, 16, v195
	v_and_b32_e32 v85, 0xffff0000, v195
	v_pk_mul_f32 v[78:79], v[78:79], v[90:91]
	v_pk_mul_f32 v[80:81], v[80:81], v[82:83]
	v_pk_mul_f32 v[82:83], v[76:77], v[84:85]
	v_pk_mul_f32 v[76:77], v[74:75], v[92:93]
	v_cvt_pk_bf16_f32 v74, v78, v79
	v_lshl_add_u64 v[78:79], s[12:13], 0, v[86:87]
	v_cvt_pk_bf16_f32 v75, v80, v81
	v_cvt_pk_bf16_f32 v76, v76, v77
	v_cvt_pk_bf16_f32 v77, v82, v83
	v_lshl_add_u64 v[78:79], v[78:79], 0, v[130:131]
	global_store_dwordx4 v[78:79], v[74:77], off
	s_nop 1
	v_lshl_add_u64 v[74:75], v[88:89], 0, v[122:123]
	global_load_dwordx4 v[180:183], v[222:223], off
	s_waitcnt vmcnt(8)
	v_lshlrev_b32_e32 v80, 16, v196
	v_and_b32_e32 v81, 0xffff0000, v196
	v_lshlrev_b32_e32 v74, 16, v197
	v_and_b32_e32 v75, 0xffff0000, v197
	v_lshlrev_b32_e32 v82, 16, v198
	v_and_b32_e32 v83, 0xffff0000, v198
	v_lshlrev_b32_e32 v76, 16, v199
	v_and_b32_e32 v77, 0xffff0000, v199
	v_pk_mul_f32 v[72:73], v[72:73], v[74:75]
	v_pk_mul_f32 v[70:71], v[70:71], v[80:81]
	v_pk_mul_f32 v[74:75], v[68:69], v[76:77]
	v_pk_mul_f32 v[68:69], v[66:67], v[82:83]
	v_cvt_pk_bf16_f32 v66, v70, v71
	v_cvt_pk_bf16_f32 v67, v72, v73
	v_cvt_pk_bf16_f32 v68, v68, v69
	v_cvt_pk_bf16_f32 v69, v74, v75
	global_store_dwordx4 v[78:79], v[66:69], off offset:256
	s_nop 1
	v_add_u32_e32 v66, 0x80, v132
	v_ashrrev_i32_e32 v67, 31, v66
	v_lshlrev_b64 v[70:71], 11, v[66:67]
	v_mad_i64_i32 v[66:67], s[0:1], v66, s24, v[134:135]
	v_lshl_add_u64 v[72:73], v[66:67], 0, s[18:19]
	v_lshl_add_u64 v[66:67], v[72:73], 0, v[130:131]
	global_load_dwordx4 v[184:187], v[226:227], off
	s_waitcnt vmcnt(8)
	v_lshlrev_b32_e32 v74, 16, v168
	v_and_b32_e32 v75, 0xffff0000, v168
	v_lshlrev_b32_e32 v66, 16, v169
	v_and_b32_e32 v67, 0xffff0000, v169
	v_lshlrev_b32_e32 v76, 16, v170
	v_and_b32_e32 v77, 0xffff0000, v170
	v_lshlrev_b32_e32 v68, 16, v171
	v_and_b32_e32 v69, 0xffff0000, v171
	v_pk_mul_f32 v[62:63], v[62:63], v[74:75]
	v_pk_mul_f32 v[64:65], v[64:65], v[66:67]
	v_pk_mul_f32 v[66:67], v[60:61], v[68:69]
	v_pk_mul_f32 v[60:61], v[58:59], v[76:77]
	v_cvt_pk_bf16_f32 v58, v62, v63
	v_lshl_add_u64 v[62:63], s[12:13], 0, v[70:71]
	v_cvt_pk_bf16_f32 v59, v64, v65
	v_cvt_pk_bf16_f32 v60, v60, v61
	v_cvt_pk_bf16_f32 v61, v66, v67
	v_lshl_add_u64 v[62:63], v[62:63], 0, v[130:131]
	global_store_dwordx4 v[62:63], v[58:61], off
	s_nop 1
	v_lshl_add_u64 v[58:59], v[72:73], 0, v[122:123]
	global_load_dwordx4 v[188:191], v[232:233], off
	s_waitcnt vmcnt(8)
	v_lshlrev_b32_e32 v64, 16, v172
	v_and_b32_e32 v65, 0xffff0000, v172
	v_lshlrev_b32_e32 v58, 16, v173
	v_and_b32_e32 v59, 0xffff0000, v173
	v_lshlrev_b32_e32 v66, 16, v174
	v_and_b32_e32 v67, 0xffff0000, v174
	v_lshlrev_b32_e32 v60, 16, v175
	v_and_b32_e32 v61, 0xffff0000, v175
	v_pk_mul_f32 v[56:57], v[56:57], v[58:59]
	v_pk_mul_f32 v[54:55], v[54:55], v[64:65]
	v_pk_mul_f32 v[58:59], v[52:53], v[60:61]
	v_pk_mul_f32 v[52:53], v[50:51], v[66:67]
	v_cvt_pk_bf16_f32 v50, v54, v55
	v_cvt_pk_bf16_f32 v51, v56, v57
	v_cvt_pk_bf16_f32 v52, v52, v53
	v_cvt_pk_bf16_f32 v53, v58, v59
	global_store_dwordx4 v[62:63], v[50:53], off offset:256
	s_nop 1
	v_add_u32_e32 v50, 0x90, v132
	v_ashrrev_i32_e32 v51, 31, v50
	v_lshlrev_b64 v[54:55], 11, v[50:51]
	v_mad_i64_i32 v[50:51], s[0:1], v50, s24, v[134:135]
	v_lshl_add_u64 v[56:57], v[50:51], 0, s[18:19]
	v_lshl_add_u64 v[50:51], v[56:57], 0, v[130:131]
	global_load_dwordx4 v[192:195], v[166:167], off
	s_waitcnt vmcnt(8)
	v_lshlrev_b32_e32 v58, 16, v176
	v_and_b32_e32 v59, 0xffff0000, v176
	v_lshlrev_b32_e32 v50, 16, v177
	v_and_b32_e32 v51, 0xffff0000, v177
	v_lshlrev_b32_e32 v60, 16, v178
	v_and_b32_e32 v61, 0xffff0000, v178
	v_lshlrev_b32_e32 v52, 16, v179
	v_and_b32_e32 v53, 0xffff0000, v179
	v_pk_mul_f32 v[46:47], v[46:47], v[58:59]
	v_pk_mul_f32 v[48:49], v[48:49], v[50:51]
	v_pk_mul_f32 v[50:51], v[44:45], v[52:53]
	v_pk_mul_f32 v[44:45], v[42:43], v[60:61]
	v_cvt_pk_bf16_f32 v42, v46, v47
	v_lshl_add_u64 v[46:47], s[12:13], 0, v[54:55]
	v_cvt_pk_bf16_f32 v43, v48, v49
	v_cvt_pk_bf16_f32 v44, v44, v45
	v_cvt_pk_bf16_f32 v45, v50, v51
	v_lshl_add_u64 v[46:47], v[46:47], 0, v[130:131]
	global_store_dwordx4 v[46:47], v[42:45], off
	s_nop 1
	v_lshl_add_u64 v[42:43], v[56:57], 0, v[122:123]
	global_load_dwordx4 v[196:199], v[252:253], off
	s_waitcnt vmcnt(8)
	v_lshlrev_b32_e32 v48, 16, v180
	v_and_b32_e32 v49, 0xffff0000, v180
	v_lshlrev_b32_e32 v42, 16, v181
	v_and_b32_e32 v43, 0xffff0000, v181
	v_lshlrev_b32_e32 v50, 16, v182
	v_and_b32_e32 v51, 0xffff0000, v182
	v_lshlrev_b32_e32 v44, 16, v183
	v_and_b32_e32 v45, 0xffff0000, v183
	v_pk_mul_f32 v[40:41], v[40:41], v[42:43]
	v_pk_mul_f32 v[38:39], v[38:39], v[48:49]
	v_pk_mul_f32 v[42:43], v[36:37], v[44:45]
	v_pk_mul_f32 v[36:37], v[34:35], v[50:51]
	v_cvt_pk_bf16_f32 v34, v38, v39
	v_cvt_pk_bf16_f32 v35, v40, v41
	v_cvt_pk_bf16_f32 v36, v36, v37
	v_cvt_pk_bf16_f32 v37, v42, v43
	global_store_dwordx4 v[46:47], v[34:37], off offset:256
	s_nop 1
	v_add_u32_e32 v34, 0xa0, v132
	v_ashrrev_i32_e32 v35, 31, v34
	v_lshlrev_b64 v[38:39], 11, v[34:35]
	v_mad_i64_i32 v[34:35], s[0:1], v34, s24, v[134:135]
	v_lshl_add_u64 v[40:41], v[34:35], 0, s[18:19]
	v_lshl_add_u64 v[34:35], v[40:41], 0, v[130:131]
	s_waitcnt vmcnt(7)
	v_lshlrev_b32_e32 v42, 16, v184
	v_and_b32_e32 v43, 0xffff0000, v184
	v_lshlrev_b32_e32 v34, 16, v185
	v_and_b32_e32 v35, 0xffff0000, v185
	v_lshlrev_b32_e32 v44, 16, v186
	v_and_b32_e32 v45, 0xffff0000, v186
	v_lshlrev_b32_e32 v36, 16, v187
	v_and_b32_e32 v37, 0xffff0000, v187
	v_pk_mul_f32 v[30:31], v[30:31], v[42:43]
	v_pk_mul_f32 v[32:33], v[32:33], v[34:35]
	v_pk_mul_f32 v[34:35], v[28:29], v[36:37]
	v_pk_mul_f32 v[28:29], v[26:27], v[44:45]
	v_cvt_pk_bf16_f32 v26, v30, v31
	v_lshl_add_u64 v[30:31], s[12:13], 0, v[38:39]
	v_cvt_pk_bf16_f32 v27, v32, v33
	v_cvt_pk_bf16_f32 v28, v28, v29
	v_cvt_pk_bf16_f32 v29, v34, v35
	v_lshl_add_u64 v[30:31], v[30:31], 0, v[130:131]
	global_store_dwordx4 v[30:31], v[26:29], off
	s_nop 1
	v_lshl_add_u64 v[26:27], v[40:41], 0, v[122:123]
	s_waitcnt vmcnt(6)
	v_lshlrev_b32_e32 v32, 16, v188
	v_and_b32_e32 v33, 0xffff0000, v188
	v_lshlrev_b32_e32 v26, 16, v189
	v_and_b32_e32 v27, 0xffff0000, v189
	v_lshlrev_b32_e32 v34, 16, v190
	v_and_b32_e32 v35, 0xffff0000, v190
	v_lshlrev_b32_e32 v28, 16, v191
	v_and_b32_e32 v29, 0xffff0000, v191
	v_pk_mul_f32 v[24:25], v[24:25], v[26:27]
	v_pk_mul_f32 v[22:23], v[22:23], v[32:33]
	v_pk_mul_f32 v[26:27], v[20:21], v[28:29]
	v_pk_mul_f32 v[20:21], v[18:19], v[34:35]
	v_cvt_pk_bf16_f32 v18, v22, v23
	v_cvt_pk_bf16_f32 v19, v24, v25
	v_cvt_pk_bf16_f32 v20, v20, v21
	v_cvt_pk_bf16_f32 v21, v26, v27
	global_store_dwordx4 v[30:31], v[18:21], off offset:256
	s_nop 1
	v_add_u32_e32 v18, 0xb0, v132
	v_ashrrev_i32_e32 v19, 31, v18
	v_lshlrev_b64 v[22:23], 11, v[18:19]
	v_mad_i64_i32 v[18:19], s[0:1], v18, s24, v[134:135]
	v_lshl_add_u64 v[24:25], v[18:19], 0, s[18:19]
	v_lshl_add_u64 v[18:19], v[24:25], 0, v[130:131]
	s_waitcnt vmcnt(5)
	s_mov_b64 s[18:19], -1
	v_lshlrev_b32_e32 v26, 16, v192
	v_and_b32_e32 v27, 0xffff0000, v192
	v_lshlrev_b32_e32 v18, 16, v193
	v_and_b32_e32 v19, 0xffff0000, v193
	v_lshlrev_b32_e32 v28, 16, v194
	v_and_b32_e32 v29, 0xffff0000, v194
	v_lshlrev_b32_e32 v20, 16, v195
	v_and_b32_e32 v21, 0xffff0000, v195
	v_pk_mul_f32 v[14:15], v[14:15], v[26:27]
	v_pk_mul_f32 v[16:17], v[16:17], v[18:19]
	v_pk_mul_f32 v[18:19], v[12:13], v[20:21]
	v_pk_mul_f32 v[12:13], v[10:11], v[28:29]
	v_cvt_pk_bf16_f32 v10, v14, v15
	v_lshl_add_u64 v[14:15], s[12:13], 0, v[22:23]
	v_cvt_pk_bf16_f32 v11, v16, v17
	v_cvt_pk_bf16_f32 v12, v12, v13
	v_cvt_pk_bf16_f32 v13, v18, v19
	v_lshl_add_u64 v[14:15], v[14:15], 0, v[130:131]
	global_store_dwordx4 v[14:15], v[10:13], off
	s_nop 1
	v_lshl_add_u64 v[10:11], v[24:25], 0, v[122:123]
	s_waitcnt vmcnt(4)
	v_lshlrev_b32_e32 v16, 16, v196
	v_and_b32_e32 v17, 0xffff0000, v196
	v_lshlrev_b32_e32 v10, 16, v197
	v_and_b32_e32 v11, 0xffff0000, v197
	v_lshlrev_b32_e32 v18, 16, v198
	v_and_b32_e32 v19, 0xffff0000, v198
	v_lshlrev_b32_e32 v12, 16, v199
	v_and_b32_e32 v13, 0xffff0000, v199
	v_pk_mul_f32 v[8:9], v[8:9], v[10:11]
	v_pk_mul_f32 v[6:7], v[6:7], v[16:17]
	v_pk_mul_f32 v[10:11], v[4:5], v[12:13]
	v_pk_mul_f32 v[4:5], v[2:3], v[18:19]
	v_cvt_pk_bf16_f32 v2, v6, v7
	v_cvt_pk_bf16_f32 v3, v8, v9
	v_cvt_pk_bf16_f32 v4, v4, v5
	v_cvt_pk_bf16_f32 v5, v10, v11
	global_store_dwordx4 v[14:15], v[2:5], off offset:256
	s_cbranch_vccnz .LBB0_243
	s_andn2_b64 vcc, exec, s[8:9]
	s_cbranch_vccnz .LBB0_242
	s_barrier
	s_branch .LBB0_242
